# the L1 invalidate (buffer_inv) after the XCC-local barriers P3-P4, P4-P5, P5-P6 and P7-P8 is dropped: in those phases no CU re-reads a line that another CU rewrote since the last invalidate (P6-P7 kee
# speedup vs baseline: 1.0054x; 1.0054x over previous
; __device__ __forceinline__ unsigned xb_ld(unsigned* p)              { return __hip_atomic_load(p, __ATOMIC_RELAXED, __HIP_MEMORY_SCOPE_AGENT); }
; __device__ __forceinline__ unsigned xb_add(unsigned* p, unsigned v) { return __hip_atomic_fetch_add(p, v, __ATOMIC_RELAXED, __HIP_MEMORY_SCOPE_AGENT); }
; #define XB_SPIN(cond, bar) do { unsigned _sp = 0; while (cond) { __builtin_amdgcn_s_sleep(1); \
;     if ((++_sp & 255u) == 0u) { if (xb_ld(&(bar)[XB_TMO])) break; if (_sp > XB_SPIN_CAP) { atomicAdd(&(bar)[XB_TMO], 1u); break; } } } } while (0)
; __device__ __forceinline__ void xcc_local_barrier(const XcdBarrier& b, unsigned nloc) {
;     asm volatile("s_waitcnt vmcnt(0)" ::: "memory");
;     __syncthreads();
;     if (threadIdx.x == 0) {
;         __builtin_amdgcn_s_waitcnt(0);
;         const unsigned old = xb_add(&b.bar[XB_LCNT(b.x)], 1u);
;         const unsigned target = (old / nloc + 1u) * nloc;
;         XB_SPIN(xb_ld(&b.bar[XB_LCNT(b.x)]) < target, b.bar);
;         __builtin_amdgcn_fence(__ATOMIC_ACQUIRE, "agent");
;         asm volatile("s_waitcnt vmcnt(0)" ::: "memory");
;     }
;     __syncthreads();
; }
.LBB0_736:
	s_or_b64 exec, exec, s[12:13]
	s_waitcnt vmcnt(0)
	s_waitcnt vmcnt(0)

; __device__ __forceinline__ unsigned xb_ld(unsigned* p)              { return __hip_atomic_load(p, __ATOMIC_RELAXED, __HIP_MEMORY_SCOPE_AGENT); }
; __device__ __forceinline__ unsigned xb_add(unsigned* p, unsigned v) { return __hip_atomic_fetch_add(p, v, __ATOMIC_RELAXED, __HIP_MEMORY_SCOPE_AGENT); }
; #define XB_SPIN(cond, bar) do { unsigned _sp = 0; while (cond) { __builtin_amdgcn_s_sleep(1); \
;     if ((++_sp & 255u) == 0u) { if (xb_ld(&(bar)[XB_TMO])) break; if (_sp > XB_SPIN_CAP) { atomicAdd(&(bar)[XB_TMO], 1u); break; } } } } while (0)
; __device__ __forceinline__ void xcc_local_barrier(const XcdBarrier& b, unsigned nloc) {
;     asm volatile("s_waitcnt vmcnt(0)" ::: "memory");
;     __syncthreads();
;     if (threadIdx.x == 0) {
;         __builtin_amdgcn_s_waitcnt(0);
;         const unsigned old = xb_add(&b.bar[XB_LCNT(b.x)], 1u);
;         const unsigned target = (old / nloc + 1u) * nloc;
;         XB_SPIN(xb_ld(&b.bar[XB_LCNT(b.x)]) < target, b.bar);
;         __builtin_amdgcn_fence(__ATOMIC_ACQUIRE, "agent");
;         asm volatile("s_waitcnt vmcnt(0)" ::: "memory");
;     }
;     __syncthreads();
; }
.LBB0_831:
	s_or_b64 exec, exec, s[10:11]
	s_waitcnt vmcnt(0)
	s_waitcnt vmcnt(0)

; __device__ __forceinline__ unsigned xb_ld(unsigned* p)              { return __hip_atomic_load(p, __ATOMIC_RELAXED, __HIP_MEMORY_SCOPE_AGENT); }
; __device__ __forceinline__ unsigned xb_add(unsigned* p, unsigned v) { return __hip_atomic_fetch_add(p, v, __ATOMIC_RELAXED, __HIP_MEMORY_SCOPE_AGENT); }
; #define XB_SPIN(cond, bar) do { unsigned _sp = 0; while (cond) { __builtin_amdgcn_s_sleep(1); \
;     if ((++_sp & 255u) == 0u) { if (xb_ld(&(bar)[XB_TMO])) break; if (_sp > XB_SPIN_CAP) { atomicAdd(&(bar)[XB_TMO], 1u); break; } } } } while (0)
; __device__ __forceinline__ void xcc_local_barrier(const XcdBarrier& b, unsigned nloc) {
;     asm volatile("s_waitcnt vmcnt(0)" ::: "memory");
;     __syncthreads();
;     if (threadIdx.x == 0) {
;         __builtin_amdgcn_s_waitcnt(0);
;         const unsigned old = xb_add(&b.bar[XB_LCNT(b.x)], 1u);
;         const unsigned target = (old / nloc + 1u) * nloc;
;         XB_SPIN(xb_ld(&b.bar[XB_LCNT(b.x)]) < target, b.bar);
;         __builtin_amdgcn_fence(__ATOMIC_ACQUIRE, "agent");
;         asm volatile("s_waitcnt vmcnt(0)" ::: "memory");
;     }
;     __syncthreads();
; }
.LBB0_913:
	s_or_b64 exec, exec, s[8:9]
	s_waitcnt vmcnt(0)
	s_waitcnt vmcnt(0)
